# MLA loop: per-step lgkmcnt(0)+s_barrier sunk from step end to just before the next step's first LDS read (overlaps LDS-write drain and barrier skew with next step's exps/QK MFMAs)
# speedup vs baseline: 1.0246x; 1.0149x over previous
.LBB0_543:
	s_add_i32 s35, s35, 2
	s_mov_b64 s[0:1], 0x2000
	s_cmpk_lt_u32 s35, 0x7e
	v_lshl_add_u64 v[226:227], v[226:227], 0, s[0:1]
	s_waitcnt vmcnt(0)
	ds_write_b128 v230, v[206:209] offset:26624
	s_cbranch_scc0 .LBB0_559

.LBB0_546:
	s_or_b64 exec, exec, s[24:25]
	global_load_dwordx4 v[206:209], v[252:253], off
	s_mov_b64 s[0:1], 0x10000
	v_lshl_add_u64 v[250:251], v[250:251], 0, s[0:1]
	v_lshl_add_u64 v[252:253], v[252:253], 0, s[0:1]
	v_exp_f32_e32 v0, v82
	v_exp_f32_e32 v34, v83
	v_mfma_f32_32x32x16_bf16 v[114:129], v[98:101], v[150:153], v[66:81]
	v_exp_f32_e32 v36, v85
	v_add_f32_e32 v35, v34, v0
	v_cvt_pk_bf16_f32 v34, v0, v34
	v_exp_f32_e32 v0, v84
	s_nop 0
	v_add_f32_e32 v35, v0, v35
	v_add_f32_e32 v37, v36, v35
	v_cvt_pk_bf16_f32 v35, v0, v36
	v_exp_f32_e32 v0, v86
	v_mfma_f32_32x32x16_bf16 v[98:113], v[202:205], v[150:153], v[66:81]
	v_exp_f32_e32 v36, v87
	v_exp_f32_e32 v38, v88
	v_exp_f32_e32 v39, v89
	v_add_f32_e32 v37, v0, v37
	v_add_f32_e32 v37, v36, v37
	v_cvt_pk_bf16_f32 v36, v0, v36
	v_add_f32_e32 v0, v38, v37
	v_add_f32_e32 v0, v39, v0
	v_cvt_pk_bf16_f32 v37, v38, v39
	v_exp_f32_e32 v38, v90
	v_exp_f32_e32 v39, v91
	v_mfma_f32_32x32x16_bf16 v[114:129], v[198:201], v[146:149], v[114:129]
	v_exp_f32_e32 v40, v93
	v_add_f32_e32 v0, v38, v0
	v_add_f32_e32 v0, v39, v0
	v_cvt_pk_bf16_f32 v38, v38, v39
	v_exp_f32_e32 v39, v92
	s_nop 0
	v_add_f32_e32 v0, v39, v0
	v_add_f32_e32 v0, v40, v0
	v_cvt_pk_bf16_f32 v39, v39, v40
	v_exp_f32_e32 v40, v94
	v_exp_f32_e32 v41, v95
	v_mfma_f32_32x32x16_bf16 v[98:113], v[194:197], v[146:149], v[98:113]
	v_exp_f32_e32 v42, v97
	v_add_f32_e32 v0, v40, v0
	v_add_f32_e32 v0, v41, v0
	v_cvt_pk_bf16_f32 v40, v40, v41
	v_exp_f32_e32 v41, v96
	s_nop 0
	v_add_f32_e32 v0, v41, v0
	v_add_f32_e32 v0, v42, v0
	v_cvt_pk_bf16_f32 v41, v41, v42
	v_mfma_f32_32x32x16_bf16 v[114:129], v[190:193], v[142:145], v[114:129]
	s_waitcnt lgkmcnt(0)
	s_barrier
	ds_read_b64_tr_b16 v[82:83], v231 offset:26624
	ds_read_b64_tr_b16 v[84:85], v231 offset:27392
	ds_read_b64_tr_b16 v[46:47], v231 offset:26688
	ds_read_b64_tr_b16 v[48:49], v231 offset:27456
	v_exp_f32_e32 v42, v50
	v_exp_f32_e32 v43, v51
	v_add_f32_e32 v0, v42, v0
	v_add_f32_e32 v0, v43, v0
	v_cvt_pk_bf16_f32 v42, v42, v43
	v_mfma_f32_32x32x16_bf16 v[98:113], v[186:189], v[142:145], v[98:113]
	v_exp_f32_e32 v43, v52
	v_exp_f32_e32 v44, v53
	ds_read_b64_tr_b16 v[86:87], v231 offset:29696
	ds_read_b64_tr_b16 v[88:89], v231 offset:30464
	v_add_f32_e32 v0, v43, v0
	v_add_f32_e32 v0, v44, v0
	v_cvt_pk_bf16_f32 v43, v43, v44
	v_mfma_f32_32x32x16_bf16 v[114:129], v[182:185], v[138:141], v[114:129]
	v_exp_f32_e32 v44, v54
	v_exp_f32_e32 v45, v55
	ds_read_b64_tr_b16 v[90:91], v231 offset:29760
	ds_read_b64_tr_b16 v[92:93], v231 offset:30528
	v_add_f32_e32 v0, v44, v0
	v_add_f32_e32 v0, v45, v0
	v_cvt_pk_bf16_f32 v44, v44, v45
	v_mfma_f32_32x32x16_bf16 v[98:113], v[178:181], v[138:141], v[98:113]
	v_exp_f32_e32 v45, v56
	v_exp_f32_e32 v50, v57
	ds_read_b64_tr_b16 v[94:95], v231 offset:32768
	ds_read_b64_tr_b16 v[96:97], v231 offset:33536
	v_add_f32_e32 v0, v45, v0
	v_add_f32_e32 v0, v50, v0
	v_cvt_pk_bf16_f32 v45, v45, v50
	v_mfma_f32_32x32x16_bf16 v[114:129], v[174:177], v[134:137], v[114:129]
	v_exp_f32_e32 v50, v58
	v_exp_f32_e32 v51, v59
	ds_read_b64_tr_b16 v[210:211], v231 offset:32832
	ds_read_b64_tr_b16 v[212:213], v231 offset:33600
	v_add_f32_e32 v0, v50, v0
	v_add_f32_e32 v0, v51, v0
	v_cvt_pk_bf16_f32 v54, v50, v51
	v_mfma_f32_32x32x16_bf16 v[98:113], v[170:173], v[134:137], v[98:113]
	v_exp_f32_e32 v50, v60
	v_exp_f32_e32 v51, v61
	ds_read_b64_tr_b16 v[58:59], v231 offset:35840
	ds_read_b64_tr_b16 v[60:61], v231 offset:36608
	v_add_f32_e32 v0, v50, v0
	v_add_f32_e32 v0, v51, v0
	v_cvt_pk_bf16_f32 v55, v50, v51
	v_mfma_f32_32x32x16_bf16 v[114:129], v[166:169], v[130:133], v[114:129]
	v_exp_f32_e32 v50, v62
	v_exp_f32_e32 v51, v63
	ds_read_b64_tr_b16 v[214:215], v231 offset:35904
	ds_read_b64_tr_b16 v[216:217], v231 offset:36672
	v_add_f32_e32 v0, v50, v0
	v_add_f32_e32 v0, v51, v0
	v_cvt_pk_bf16_f32 v56, v50, v51
	v_mfma_f32_32x32x16_bf16 v[98:113], v[158:161], v[130:133], v[98:113]
	v_exp_f32_e32 v50, v64
	v_exp_f32_e32 v51, v65
	v_add_f32_e32 v0, v50, v0
	v_add_f32_e32 v62, v51, v0
	v_cvt_pk_bf16_f32 v57, v50, v51
	s_waitcnt lgkmcnt(14)
	v_mfma_f32_32x32x16_bf16 v[18:33], v[82:85], v[34:37], v[18:33]
	ds_read_b128 v[50:53], v233
	ds_read_b128 v[198:201], v233 offset:6656
	v_add_f32_e32 v0, v242, v62
	s_waitcnt lgkmcnt(14)
	v_mfma_f32_32x32x16_bf16 v[2:17], v[46:49], v[34:37], v[2:17]
	ds_read_b128 v[202:205], v233 offset:32
	ds_read_b128 v[194:197], v233 offset:6688
	s_waitcnt lgkmcnt(14)
	v_mfma_f32_32x32x16_bf16 v[18:33], v[86:89], v[38:41], v[18:33]
	ds_read_b128 v[190:193], v233 offset:64
	ds_read_b128 v[186:189], v233 offset:6720
	s_waitcnt lgkmcnt(14)
	v_mfma_f32_32x32x16_bf16 v[2:17], v[90:93], v[38:41], v[2:17]
	ds_read_b128 v[182:185], v233 offset:96
	ds_read_b128 v[178:181], v233 offset:6752
	s_waitcnt lgkmcnt(14)
	v_mfma_f32_32x32x16_bf16 v[18:33], v[94:97], v[42:45], v[18:33]
	ds_read_b128 v[174:177], v233 offset:128
	ds_read_b128 v[170:173], v233 offset:6784
	s_waitcnt lgkmcnt(14)
	v_mfma_f32_32x32x16_bf16 v[2:17], v[210:213], v[42:45], v[2:17]
	ds_read_b128 v[166:169], v233 offset:160
	ds_read_b128 v[158:161], v233 offset:6816
	s_waitcnt lgkmcnt(14)
	v_mfma_f32_32x32x16_bf16 v[18:33], v[58:61], v[54:57], v[18:33]
	s_waitcnt lgkmcnt(12)
	v_mfma_f32_32x32x16_bf16 v[2:17], v[214:217], v[54:57], v[2:17]
	v_mov_b32_e32 v34, v62
	s_nop 1
	v_permlane32_swap_b32_e32 v62, v34
	v_max_f32_e32 v34, v62, v34
	v_cmp_lt_f32_e32 vcc, s74, v34
	s_cbranch_vccz .LBB0_558
	v_frexp_exp_i32_f32_e32 v34, v34
	v_cvt_f32_i32_e32 v34, v34
	v_cndmask_b32_e32 v35, 0, v34, vcc
	v_exp_f32_e64 v36, -v35
	v_add_f32_e32 v235, v235, v35
	v_xor_b32_e32 v34, 0x80000000, v235
	v_sub_f32_e32 v129, v129, v35
	v_pk_mul_f32 v[32:33], v[32:33], v[36:37] op_sel_hi:[1,0]
	v_pk_mul_f32 v[30:31], v[30:31], v[36:37] op_sel_hi:[1,0]
	v_pk_mul_f32 v[28:29], v[28:29], v[36:37] op_sel_hi:[1,0]
	v_pk_mul_f32 v[26:27], v[26:27], v[36:37] op_sel_hi:[1,0]
	v_pk_mul_f32 v[24:25], v[24:25], v[36:37] op_sel_hi:[1,0]
	v_pk_mul_f32 v[22:23], v[22:23], v[36:37] op_sel_hi:[1,0]
	v_pk_mul_f32 v[20:21], v[20:21], v[36:37] op_sel_hi:[1,0]
	v_pk_mul_f32 v[18:19], v[18:19], v[36:37] op_sel_hi:[1,0]
	v_pk_mul_f32 v[16:17], v[16:17], v[36:37] op_sel_hi:[1,0]
	v_pk_mul_f32 v[14:15], v[14:15], v[36:37] op_sel_hi:[1,0]
	v_pk_mul_f32 v[12:13], v[12:13], v[36:37] op_sel_hi:[1,0]
	v_pk_mul_f32 v[10:11], v[10:11], v[36:37] op_sel_hi:[1,0]
	v_pk_mul_f32 v[8:9], v[8:9], v[36:37] op_sel_hi:[1,0]
	v_pk_mul_f32 v[6:7], v[6:7], v[36:37] op_sel_hi:[1,0]
	v_pk_mul_f32 v[4:5], v[4:5], v[36:37] op_sel_hi:[1,0]
	v_pk_mul_f32 v[2:3], v[2:3], v[36:37] op_sel_hi:[1,0]
	v_sub_f32_e32 v128, v128, v35
	v_sub_f32_e32 v127, v127, v35
	v_sub_f32_e32 v126, v126, v35
	v_sub_f32_e32 v125, v125, v35
	v_sub_f32_e32 v124, v124, v35
	v_sub_f32_e32 v123, v123, v35
	v_sub_f32_e32 v122, v122, v35
	v_sub_f32_e32 v121, v121, v35
	v_sub_f32_e32 v120, v120, v35
	v_sub_f32_e32 v119, v119, v35
	v_sub_f32_e32 v118, v118, v35
	v_sub_f32_e32 v117, v117, v35
	v_sub_f32_e32 v116, v116, v35
	v_sub_f32_e32 v115, v115, v35
	v_sub_f32_e32 v114, v114, v35
	v_sub_f32_e32 v113, v113, v35
	v_sub_f32_e32 v112, v112, v35
	v_sub_f32_e32 v111, v111, v35
	v_sub_f32_e32 v110, v110, v35
	v_sub_f32_e32 v109, v109, v35
	v_sub_f32_e32 v108, v108, v35
	v_sub_f32_e32 v107, v107, v35
	v_sub_f32_e32 v106, v106, v35
	v_sub_f32_e32 v105, v105, v35
	v_sub_f32_e32 v104, v104, v35
	v_sub_f32_e32 v103, v103, v35
	v_sub_f32_e32 v102, v102, v35
	v_sub_f32_e32 v101, v101, v35
	v_sub_f32_e32 v100, v100, v35
	v_sub_f32_e32 v99, v99, v35
	v_sub_f32_e32 v98, v98, v35
	v_mul_f32_e32 v0, v0, v36
	v_mov_b32_e32 v35, v34
	v_mov_b32_e32 v36, v34
	v_mov_b32_e32 v37, v34
	v_mov_b32_e32 v38, v34
	v_mov_b32_e32 v39, v34
	v_mov_b32_e32 v40, v34
	v_mov_b32_e32 v41, v34
	v_mov_b32_e32 v42, v34
	v_mov_b32_e32 v43, v34
	v_mov_b32_e32 v44, v34
	v_mov_b32_e32 v45, v34
	v_mov_b32_e32 v46, v34
	v_mov_b32_e32 v47, v34
	v_mov_b32_e32 v48, v34
	v_mov_b32_e32 v49, v34
	v_mov_b32_e32 v66, v34
	v_mov_b32_e32 v67, v34
	v_mov_b32_e32 v68, v34
	v_mov_b32_e32 v69, v34
	v_mov_b32_e32 v70, v34
	v_mov_b32_e32 v71, v34
	v_mov_b32_e32 v72, v34
	v_mov_b32_e32 v73, v34
	v_mov_b32_e32 v74, v34
	v_mov_b32_e32 v75, v34
	v_mov_b32_e32 v76, v34
	v_mov_b32_e32 v77, v34
	v_mov_b32_e32 v78, v34
	v_mov_b32_e32 v79, v34
	v_mov_b32_e32 v80, v34
	v_mov_b32_e32 v81, v34
	s_waitcnt vmcnt(1)
	ds_write_b128 v232, v[162:165] offset:13312
	s_and_saveexec_b64 s[24:25], s[4:5]

.LBB0_549:
	s_or_b64 exec, exec, s[24:25]
	s_cmpk_lt_u32 s35, 0x7c
	s_cselect_b64 s[24:25], -1, 0
	s_cmpk_gt_u32 s35, 0x7b
	s_waitcnt vmcnt(0)
	ds_write_b128 v234, v[206:209] offset:38912
	s_cbranch_scc1 .LBB0_553
	global_load_dwordx4 v[162:165], v[250:251], off
	s_and_saveexec_b64 s[26:27], s[4:5]
	s_cbranch_execz .LBB0_552
	v_lshl_add_u64 v[54:55], v[226:227], 0, s[70:71]
	v_add_co_u32_e32 v54, vcc, 0x15e04000, v54
	s_nop 1
	v_addc_co_u32_e32 v55, vcc, 0, v55, vcc
	global_load_dwordx4 v[154:157], v[54:55], off

.LBB0_553:
	global_load_dwordx4 v[206:209], v[252:253], off
	s_mov_b64 s[0:1], 0x10000
	v_lshl_add_u64 v[250:251], v[250:251], 0, s[0:1]
	v_lshl_add_u64 v[252:253], v[252:253], 0, s[0:1]
	v_mfma_f32_32x32x16_bf16 v[82:97], v[50:53], v[150:153], v[66:81]
	v_exp_f32_e32 v50, v114
	v_exp_f32_e32 v51, v115
	v_add_f32_e32 v52, 0, v50
	v_cvt_pk_bf16_f32 v114, v50, v51
	v_exp_f32_e32 v50, v116
	v_add_f32_e32 v52, v51, v52
	v_exp_f32_e32 v51, v117
	v_add_f32_e32 v52, v50, v52
	v_add_f32_e32 v52, v51, v52
	v_cvt_pk_bf16_f32 v115, v50, v51
	v_exp_f32_e32 v116, v118
	v_exp_f32_e32 v117, v119
	v_exp_f32_e32 v118, v120
	v_exp_f32_e32 v119, v121
	v_add_f32_e32 v50, v116, v52
	v_add_f32_e32 v120, v117, v50
	v_mfma_f32_32x32x16_bf16 v[50:65], v[198:201], v[150:153], v[66:81]
	v_cvt_pk_bf16_f32 v116, v116, v117
	v_add_f32_e32 v117, v118, v120
	v_add_f32_e32 v120, v119, v117
	v_cvt_pk_bf16_f32 v117, v118, v119
	v_exp_f32_e32 v118, v122
	v_exp_f32_e32 v119, v123
	v_mfma_f32_32x32x16_bf16 v[82:97], v[202:205], v[146:149], v[82:97]
	v_exp_f32_e32 v121, v125
	v_add_f32_e32 v120, v118, v120
	v_add_f32_e32 v120, v119, v120
	v_cvt_pk_bf16_f32 v118, v118, v119
	v_exp_f32_e32 v119, v124
	s_nop 0
	v_add_f32_e32 v120, v119, v120
	v_add_f32_e32 v120, v121, v120
	v_cvt_pk_bf16_f32 v119, v119, v121
	v_exp_f32_e32 v121, v126
	v_exp_f32_e32 v122, v127
	v_mfma_f32_32x32x16_bf16 v[50:65], v[194:197], v[146:149], v[50:65]
	v_add_f32_e32 v120, v121, v120
	v_add_f32_e32 v123, v122, v120
	v_cvt_pk_bf16_f32 v120, v121, v122
	v_exp_f32_e32 v121, v128
	v_exp_f32_e32 v122, v129
	v_add_f32_e32 v123, v121, v123
	v_add_f32_e32 v123, v122, v123
	v_cvt_pk_bf16_f32 v121, v121, v122
	v_mfma_f32_32x32x16_bf16 v[82:97], v[190:193], v[142:145], v[82:97]
	s_waitcnt lgkmcnt(0)
	s_barrier
	ds_read_b64_tr_b16 v[190:191], v231 offset:38912
	ds_read_b64_tr_b16 v[192:193], v231 offset:39680
	ds_read_b64_tr_b16 v[126:127], v231 offset:38976
	ds_read_b64_tr_b16 v[128:129], v231 offset:39744
	v_exp_f32_e32 v98, v98
	v_exp_f32_e32 v99, v99
	v_add_f32_e32 v122, v98, v123
	v_add_f32_e32 v123, v99, v122
	v_cvt_pk_bf16_f32 v122, v98, v99
	v_mfma_f32_32x32x16_bf16 v[50:65], v[186:189], v[142:145], v[50:65]
	v_exp_f32_e32 v98, v100
	v_exp_f32_e32 v99, v101
	ds_read_b64_tr_b16 v[186:187], v231 offset:41984
	ds_read_b64_tr_b16 v[188:189], v231 offset:42752
	v_add_f32_e32 v100, v98, v123
	v_add_f32_e32 v100, v99, v100
	v_cvt_pk_bf16_f32 v123, v98, v99
	v_mfma_f32_32x32x16_bf16 v[82:97], v[182:185], v[138:141], v[82:97]
	v_exp_f32_e32 v98, v102
	v_exp_f32_e32 v99, v103
	ds_read_b64_tr_b16 v[182:183], v231 offset:42048
	ds_read_b64_tr_b16 v[184:185], v231 offset:42816
	v_add_f32_e32 v100, v98, v100
	v_add_f32_e32 v100, v99, v100
	v_cvt_pk_bf16_f32 v124, v98, v99
	v_mfma_f32_32x32x16_bf16 v[50:65], v[178:181], v[138:141], v[50:65]
	v_exp_f32_e32 v98, v104
	v_exp_f32_e32 v99, v105
	ds_read_b64_tr_b16 v[210:211], v231 offset:45056
	ds_read_b64_tr_b16 v[212:213], v231 offset:45824
	v_add_f32_e32 v100, v98, v100
	v_add_f32_e32 v100, v99, v100
	v_cvt_pk_bf16_f32 v125, v98, v99
	v_mfma_f32_32x32x16_bf16 v[82:97], v[174:177], v[134:137], v[82:97]
	v_exp_f32_e32 v98, v106
	v_exp_f32_e32 v99, v107
	ds_read_b64_tr_b16 v[214:215], v231 offset:45120
	ds_read_b64_tr_b16 v[216:217], v231 offset:45888
	v_add_f32_e32 v100, v98, v100
	v_add_f32_e32 v100, v99, v100
	v_cvt_pk_bf16_f32 v102, v98, v99
	v_mfma_f32_32x32x16_bf16 v[50:65], v[170:173], v[134:137], v[50:65]
	v_exp_f32_e32 v98, v108
	v_exp_f32_e32 v99, v109
	ds_read_b64_tr_b16 v[106:107], v231 offset:48128
	ds_read_b64_tr_b16 v[108:109], v231 offset:48896
	v_add_f32_e32 v100, v98, v100
	v_add_f32_e32 v100, v99, v100
	v_cvt_pk_bf16_f32 v103, v98, v99
	v_mfma_f32_32x32x16_bf16 v[82:97], v[166:169], v[130:133], v[82:97]
	v_exp_f32_e32 v98, v110
	v_exp_f32_e32 v99, v111
	ds_read_b64_tr_b16 v[244:245], v231 offset:48192
	ds_read_b64_tr_b16 v[246:247], v231 offset:48960
	v_add_f32_e32 v100, v98, v100
	v_add_f32_e32 v100, v99, v100
	v_cvt_pk_bf16_f32 v104, v98, v99
	v_mfma_f32_32x32x16_bf16 v[50:65], v[158:161], v[130:133], v[50:65]
	v_exp_f32_e32 v98, v112
	v_exp_f32_e32 v99, v113
	v_add_f32_e32 v100, v98, v100
	v_add_f32_e32 v110, v99, v100
	v_cvt_pk_bf16_f32 v105, v98, v99
	s_waitcnt lgkmcnt(14)
	v_mfma_f32_32x32x16_bf16 v[18:33], v[190:193], v[114:117], v[18:33]
	ds_read_b128 v[98:101], v233 offset:13312
	ds_read_b128 v[202:205], v233 offset:19968
	v_add_f32_e32 v242, v0, v110
	s_waitcnt lgkmcnt(14)
	v_mfma_f32_32x32x16_bf16 v[2:17], v[126:129], v[114:117], v[2:17]
	ds_read_b128 v[198:201], v233 offset:13344
	ds_read_b128 v[194:197], v233 offset:20000
	s_waitcnt lgkmcnt(14)
	v_mfma_f32_32x32x16_bf16 v[18:33], v[186:189], v[118:121], v[18:33]
	ds_read_b128 v[190:193], v233 offset:13376
	ds_read_b128 v[186:189], v233 offset:20032
	s_waitcnt lgkmcnt(14)
	v_mfma_f32_32x32x16_bf16 v[2:17], v[182:185], v[118:121], v[2:17]
	ds_read_b128 v[182:185], v233 offset:13408
	ds_read_b128 v[178:181], v233 offset:20064
	s_waitcnt lgkmcnt(14)
	v_mfma_f32_32x32x16_bf16 v[18:33], v[210:213], v[122:125], v[18:33]
	ds_read_b128 v[174:177], v233 offset:13440
	ds_read_b128 v[170:173], v233 offset:20096
	s_waitcnt lgkmcnt(14)
	v_mfma_f32_32x32x16_bf16 v[2:17], v[214:217], v[122:125], v[2:17]
	ds_read_b128 v[166:169], v233 offset:13472
	ds_read_b128 v[158:161], v233 offset:20128
	s_waitcnt lgkmcnt(14)
	v_mfma_f32_32x32x16_bf16 v[18:33], v[106:109], v[102:105], v[18:33]
	s_waitcnt lgkmcnt(12)
	v_mfma_f32_32x32x16_bf16 v[2:17], v[244:247], v[102:105], v[2:17]
	v_mov_b32_e32 v0, v110
	s_nop 1
	v_permlane32_swap_b32_e32 v110, v0
	v_max_f32_e32 v0, v110, v0
	v_cmp_lt_f32_e32 vcc, s74, v0
	s_cbranch_vccz .LBB0_555
	v_frexp_exp_i32_f32_e32 v0, v0
	v_cvt_f32_i32_e32 v0, v0
	v_cndmask_b32_e32 v35, 0, v0, vcc
	v_exp_f32_e64 v0, -v35
	v_add_f32_e32 v235, v235, v35
	v_xor_b32_e32 v34, 0x80000000, v235
	v_sub_f32_e32 v97, v97, v35
	v_pk_mul_f32 v[32:33], v[32:33], v[0:1] op_sel_hi:[1,0]
	v_pk_mul_f32 v[30:31], v[30:31], v[0:1] op_sel_hi:[1,0]
	v_pk_mul_f32 v[28:29], v[28:29], v[0:1] op_sel_hi:[1,0]
	v_pk_mul_f32 v[26:27], v[26:27], v[0:1] op_sel_hi:[1,0]
	v_pk_mul_f32 v[24:25], v[24:25], v[0:1] op_sel_hi:[1,0]
	v_pk_mul_f32 v[22:23], v[22:23], v[0:1] op_sel_hi:[1,0]
	v_pk_mul_f32 v[20:21], v[20:21], v[0:1] op_sel_hi:[1,0]
	v_pk_mul_f32 v[18:19], v[18:19], v[0:1] op_sel_hi:[1,0]
	v_pk_mul_f32 v[16:17], v[16:17], v[0:1] op_sel_hi:[1,0]
	v_pk_mul_f32 v[14:15], v[14:15], v[0:1] op_sel_hi:[1,0]
	v_pk_mul_f32 v[12:13], v[12:13], v[0:1] op_sel_hi:[1,0]
	v_pk_mul_f32 v[10:11], v[10:11], v[0:1] op_sel_hi:[1,0]
	v_pk_mul_f32 v[8:9], v[8:9], v[0:1] op_sel_hi:[1,0]
	v_pk_mul_f32 v[6:7], v[6:7], v[0:1] op_sel_hi:[1,0]
	v_pk_mul_f32 v[4:5], v[4:5], v[0:1] op_sel_hi:[1,0]
	v_pk_mul_f32 v[2:3], v[2:3], v[0:1] op_sel_hi:[1,0]
	v_sub_f32_e32 v96, v96, v35
	v_sub_f32_e32 v95, v95, v35
	v_sub_f32_e32 v94, v94, v35
	v_sub_f32_e32 v93, v93, v35
	v_sub_f32_e32 v92, v92, v35
	v_sub_f32_e32 v91, v91, v35
	v_sub_f32_e32 v90, v90, v35
	v_sub_f32_e32 v89, v89, v35
	v_sub_f32_e32 v88, v88, v35
	v_sub_f32_e32 v87, v87, v35
	v_sub_f32_e32 v86, v86, v35
	v_sub_f32_e32 v85, v85, v35
	v_sub_f32_e32 v84, v84, v35
	v_sub_f32_e32 v83, v83, v35
	v_sub_f32_e32 v82, v82, v35
	v_sub_f32_e32 v65, v65, v35
	v_sub_f32_e32 v64, v64, v35
	v_sub_f32_e32 v63, v63, v35
	v_sub_f32_e32 v62, v62, v35
	v_sub_f32_e32 v61, v61, v35
	v_sub_f32_e32 v60, v60, v35
	v_sub_f32_e32 v59, v59, v35
	v_sub_f32_e32 v58, v58, v35
	v_sub_f32_e32 v57, v57, v35
	v_sub_f32_e32 v56, v56, v35
	v_sub_f32_e32 v55, v55, v35
	v_sub_f32_e32 v54, v54, v35
	v_sub_f32_e32 v53, v53, v35
	v_sub_f32_e32 v52, v52, v35
	v_sub_f32_e32 v51, v51, v35
	v_sub_f32_e32 v50, v50, v35
	v_mul_f32_e32 v242, v242, v0
	v_mov_b32_e32 v35, v34
	v_mov_b32_e32 v36, v34
	v_mov_b32_e32 v37, v34
	v_mov_b32_e32 v38, v34
	v_mov_b32_e32 v39, v34
	v_mov_b32_e32 v40, v34
	v_mov_b32_e32 v41, v34
	v_mov_b32_e32 v42, v34
	v_mov_b32_e32 v43, v34
	v_mov_b32_e32 v44, v34
	v_mov_b32_e32 v45, v34
	v_mov_b32_e32 v46, v34
	v_mov_b32_e32 v47, v34
	v_mov_b32_e32 v48, v34
	v_mov_b32_e32 v49, v34
	v_mov_b32_e32 v66, v34
	v_mov_b32_e32 v67, v34
	v_mov_b32_e32 v68, v34
	v_mov_b32_e32 v69, v34
	v_mov_b32_e32 v70, v34
	v_mov_b32_e32 v71, v34
	v_mov_b32_e32 v72, v34
	v_mov_b32_e32 v73, v34
	v_mov_b32_e32 v74, v34
	v_mov_b32_e32 v75, v34
	v_mov_b32_e32 v76, v34
	v_mov_b32_e32 v77, v34
	v_mov_b32_e32 v78, v34
	v_mov_b32_e32 v79, v34
	v_mov_b32_e32 v80, v34
	v_mov_b32_e32 v81, v34

.LBB0_559:
	v_mov_b64_e32 v[34:35], v[66:67]
	v_mov_b64_e32 v[36:37], v[68:69]
	v_mov_b64_e32 v[38:39], v[70:71]
	v_mov_b64_e32 v[40:41], v[72:73]
	v_mov_b64_e32 v[42:43], v[74:75]
	v_mov_b64_e32 v[44:45], v[76:77]
	v_mov_b64_e32 v[46:47], v[78:79]
	v_mov_b64_e32 v[48:49], v[80:81]
	v_add_co_u32_e32 v66, vcc, 0x7f0000, v222
	s_nop 1
	v_addc_co_u32_e32 v67, vcc, 0, v223, vcc
	global_load_dwordx4 v[102:105], v[66:67], off
	v_exp_f32_e32 v0, v82
	v_exp_f32_e32 v82, v83
	v_mfma_f32_32x32x16_bf16 v[66:81], v[98:101], v[150:153], v[34:49]
	v_add_f32_e32 v83, 0, v0
	v_add_f32_e32 v83, v82, v83
	v_cvt_pk_bf16_f32 v82, v0, v82
	v_exp_f32_e32 v0, v84
	v_exp_f32_e32 v84, v85
	v_add_f32_e32 v83, v0, v83
	v_add_f32_e32 v85, v84, v83
	v_cvt_pk_bf16_f32 v83, v0, v84
	v_exp_f32_e32 v0, v86
	v_exp_f32_e32 v84, v87
	v_mfma_f32_32x32x16_bf16 v[34:49], v[202:205], v[150:153], v[34:49]
	v_exp_f32_e32 v86, v89
	v_add_f32_e32 v85, v0, v85
	v_add_f32_e32 v85, v84, v85
	v_cvt_pk_bf16_f32 v84, v0, v84
	v_exp_f32_e32 v0, v88
	s_nop 0
	v_add_f32_e32 v85, v0, v85
	v_add_f32_e32 v87, v86, v85
	v_cvt_pk_bf16_f32 v85, v0, v86
	v_exp_f32_e32 v0, v90
	v_exp_f32_e32 v86, v91
	v_mfma_f32_32x32x16_bf16 v[66:81], v[198:201], v[146:149], v[66:81]
	v_exp_f32_e32 v88, v93
	v_add_f32_e32 v87, v0, v87
	v_add_f32_e32 v87, v86, v87
	v_cvt_pk_bf16_f32 v86, v0, v86
	v_exp_f32_e32 v0, v92
	s_nop 0
	v_add_f32_e32 v87, v0, v87
	v_add_f32_e32 v89, v88, v87
	v_cvt_pk_bf16_f32 v87, v0, v88
	v_exp_f32_e32 v0, v94
	v_exp_f32_e32 v88, v95
	v_mfma_f32_32x32x16_bf16 v[34:49], v[194:197], v[146:149], v[34:49]
	v_exp_f32_e32 v90, v97
	v_add_f32_e32 v89, v0, v89
	v_add_f32_e32 v89, v88, v89
	v_cvt_pk_bf16_f32 v88, v0, v88
	v_exp_f32_e32 v0, v96
	s_nop 0
	v_add_f32_e32 v89, v0, v89
	v_add_f32_e32 v91, v90, v89
	v_cvt_pk_bf16_f32 v89, v0, v90
	v_exp_f32_e32 v0, v50
	v_mfma_f32_32x32x16_bf16 v[66:81], v[190:193], v[142:145], v[66:81]
	v_exp_f32_e32 v50, v51
	v_add_f32_e32 v51, v0, v91
	s_waitcnt lgkmcnt(0)
	s_barrier
	ds_read_b64_tr_b16 v[94:95], v231 offset:26624
	ds_read_b64_tr_b16 v[96:97], v231 offset:27392
	ds_read_b64_tr_b16 v[90:91], v231 offset:26688
	ds_read_b64_tr_b16 v[92:93], v231 offset:27456
	v_add_f32_e32 v51, v50, v51
	v_cvt_pk_bf16_f32 v50, v0, v50
	v_mfma_f32_32x32x16_bf16 v[34:49], v[186:189], v[142:145], v[34:49]
	v_exp_f32_e32 v0, v52
	ds_read_b64_tr_b16 v[98:99], v231 offset:29696
	ds_read_b64_tr_b16 v[100:101], v231 offset:30464
	v_exp_f32_e32 v52, v53
	v_add_f32_e32 v51, v0, v51
	v_add_f32_e32 v53, v52, v51
	v_cvt_pk_bf16_f32 v51, v0, v52
	v_mfma_f32_32x32x16_bf16 v[66:81], v[182:185], v[138:141], v[66:81]
	v_exp_f32_e32 v0, v54
	ds_read_b64_tr_b16 v[106:107], v231 offset:29760
	ds_read_b64_tr_b16 v[108:109], v231 offset:30528
	v_exp_f32_e32 v52, v55
	v_add_f32_e32 v53, v0, v53
	v_add_f32_e32 v53, v52, v53
	v_cvt_pk_bf16_f32 v52, v0, v52
	v_exp_f32_e32 v0, v56
	v_exp_f32_e32 v54, v57
	v_mfma_f32_32x32x16_bf16 v[34:49], v[178:181], v[138:141], v[34:49]
	v_add_f32_e32 v53, v0, v53
	v_add_f32_e32 v110, v54, v53
	v_cvt_pk_bf16_f32 v53, v0, v54
	ds_read_b64_tr_b16 v[54:55], v231 offset:32768
	ds_read_b64_tr_b16 v[56:57], v231 offset:33536
	v_exp_f32_e32 v0, v58
	v_mfma_f32_32x32x16_bf16 v[66:81], v[174:177], v[134:137], v[66:81]
	v_exp_f32_e32 v58, v59
	v_add_f32_e32 v59, v0, v110
	ds_read_b64_tr_b16 v[110:111], v231 offset:32832
	ds_read_b64_tr_b16 v[112:113], v231 offset:33600
	v_add_f32_e32 v59, v58, v59
	v_cvt_pk_bf16_f32 v58, v0, v58
	v_mfma_f32_32x32x16_bf16 v[34:49], v[170:173], v[134:137], v[34:49]
	v_exp_f32_e32 v0, v60
	ds_read_b64_tr_b16 v[114:115], v231 offset:35840
	ds_read_b64_tr_b16 v[116:117], v231 offset:36608
	v_exp_f32_e32 v60, v61
	v_add_f32_e32 v59, v0, v59
	v_add_f32_e32 v61, v60, v59
	v_cvt_pk_bf16_f32 v59, v0, v60
	v_mfma_f32_32x32x16_bf16 v[66:81], v[166:169], v[130:133], v[66:81]
	v_exp_f32_e32 v0, v62
	ds_read_b64_tr_b16 v[118:119], v231 offset:35904
	ds_read_b64_tr_b16 v[120:121], v231 offset:36672
	v_exp_f32_e32 v60, v63
	v_add_f32_e32 v61, v0, v61
	v_add_f32_e32 v61, v60, v61
	v_cvt_pk_bf16_f32 v60, v0, v60
	v_mfma_f32_32x32x16_bf16 v[34:49], v[158:161], v[130:133], v[34:49]
	v_exp_f32_e32 v0, v64
	v_exp_f32_e32 v62, v65
	v_add_f32_e32 v61, v0, v61
	v_add_f32_e32 v63, v62, v61
	v_cvt_pk_bf16_f32 v61, v0, v62
	s_waitcnt lgkmcnt(14)
	v_mfma_f32_32x32x16_bf16 v[18:33], v[94:97], v[82:85], v[18:33]
	v_add_f32_e32 v0, v242, v63
	s_waitcnt lgkmcnt(12)
	v_mfma_f32_32x32x16_bf16 v[2:17], v[90:93], v[82:85], v[2:17]
	s_waitcnt lgkmcnt(10)
	v_mfma_f32_32x32x16_bf16 v[18:33], v[98:101], v[86:89], v[18:33]
	s_waitcnt lgkmcnt(8)
	v_mfma_f32_32x32x16_bf16 v[2:17], v[106:109], v[86:89], v[2:17]
	s_waitcnt lgkmcnt(6)
	v_mfma_f32_32x32x16_bf16 v[18:33], v[54:57], v[50:53], v[18:33]
	s_waitcnt lgkmcnt(4)
	v_mfma_f32_32x32x16_bf16 v[2:17], v[110:113], v[50:53], v[2:17]
	s_waitcnt lgkmcnt(2)
	v_mfma_f32_32x32x16_bf16 v[18:33], v[114:117], v[58:61], v[18:33]
	s_waitcnt lgkmcnt(0)
	v_mfma_f32_32x32x16_bf16 v[2:17], v[118:121], v[58:61], v[2:17]
	v_mov_b32_e32 v50, v63
	s_nop 1
	v_permlane32_swap_b32_e32 v63, v50
	v_max_f32_e32 v50, v50, v50
	v_max_f32_e32 v51, v63, v63
	v_max_f32_e32 v50, v51, v50
	v_cmp_lt_f32_e32 vcc, s74, v50
	s_cbranch_vccz .LBB0_524
	v_frexp_exp_i32_f32_e32 v50, v50
	v_cvt_f32_i32_e32 v50, v50
	v_cndmask_b32_e32 v51, 0, v50, vcc
	v_exp_f32_e64 v50, -v51
	v_sub_f32_e32 v81, v81, v51
	v_sub_f32_e32 v80, v80, v51
	v_sub_f32_e32 v79, v79, v51
	v_pk_mul_f32 v[32:33], v[32:33], v[50:51] op_sel_hi:[1,0]
	v_pk_mul_f32 v[30:31], v[30:31], v[50:51] op_sel_hi:[1,0]
	v_pk_mul_f32 v[28:29], v[28:29], v[50:51] op_sel_hi:[1,0]
	v_pk_mul_f32 v[26:27], v[26:27], v[50:51] op_sel_hi:[1,0]
	v_pk_mul_f32 v[24:25], v[24:25], v[50:51] op_sel_hi:[1,0]
	v_pk_mul_f32 v[22:23], v[22:23], v[50:51] op_sel_hi:[1,0]
	v_pk_mul_f32 v[20:21], v[20:21], v[50:51] op_sel_hi:[1,0]
	v_pk_mul_f32 v[18:19], v[18:19], v[50:51] op_sel_hi:[1,0]
	v_pk_mul_f32 v[16:17], v[16:17], v[50:51] op_sel_hi:[1,0]
	v_pk_mul_f32 v[14:15], v[14:15], v[50:51] op_sel_hi:[1,0]
	v_pk_mul_f32 v[12:13], v[12:13], v[50:51] op_sel_hi:[1,0]
	v_pk_mul_f32 v[10:11], v[10:11], v[50:51] op_sel_hi:[1,0]
	v_pk_mul_f32 v[8:9], v[8:9], v[50:51] op_sel_hi:[1,0]
	v_pk_mul_f32 v[6:7], v[6:7], v[50:51] op_sel_hi:[1,0]
	v_pk_mul_f32 v[4:5], v[4:5], v[50:51] op_sel_hi:[1,0]
	v_pk_mul_f32 v[2:3], v[2:3], v[50:51] op_sel_hi:[1,0]
	v_sub_f32_e32 v78, v78, v51
	v_sub_f32_e32 v77, v77, v51
	v_sub_f32_e32 v76, v76, v51
	v_sub_f32_e32 v75, v75, v51
	v_sub_f32_e32 v74, v74, v51
	v_sub_f32_e32 v73, v73, v51
	v_sub_f32_e32 v72, v72, v51
	v_sub_f32_e32 v71, v71, v51
	v_sub_f32_e32 v70, v70, v51
	v_sub_f32_e32 v69, v69, v51
	v_sub_f32_e32 v68, v68, v51
	v_sub_f32_e32 v67, v67, v51
	v_sub_f32_e32 v66, v66, v51
	v_sub_f32_e32 v49, v49, v51
	v_sub_f32_e32 v48, v48, v51
	v_sub_f32_e32 v47, v47, v51
	v_sub_f32_e32 v46, v46, v51
	v_sub_f32_e32 v45, v45, v51
	v_sub_f32_e32 v44, v44, v51
	v_sub_f32_e32 v43, v43, v51
	v_sub_f32_e32 v42, v42, v51
	v_sub_f32_e32 v41, v41, v51
	v_sub_f32_e32 v40, v40, v51
	v_sub_f32_e32 v39, v39, v51
	v_sub_f32_e32 v38, v38, v51
	v_sub_f32_e32 v37, v37, v51
	v_sub_f32_e32 v36, v36, v51
	v_sub_f32_e32 v35, v35, v51
	v_sub_f32_e32 v34, v34, v51
	v_mul_f32_e32 v0, v0, v50
	s_branch .LBB0_524
